# P3 epilogue and K=512 rescale: blanket vmcnt(0) after the 16 gate loads replaced by counted waits at first use
# speedup vs baseline: 1.0027x; 1.0027x over previous
.LBB0_527:
	v_mov_b32_e32 v1, v222
	v_mov_b32_e32 v2, v197
	s_and_b64 vcc, exec, s[0:1]
	v_add_u32_e32 v132, s15, v2
	v_lshl_add_u32 v2, v1, 3, s47
	v_ashrrev_i32_e32 v3, 31, v2
	v_lshlrev_b64 v[2:3], 1, v[2:3]
	v_ashrrev_i32_e32 v133, 31, v132
	v_lshl_add_u64 v[134:135], s[4:5], 0, v[2:3]
	v_lshlrev_b64 v[136:137], 12, v[132:133]
	v_lshl_add_u64 v[136:137], v[134:135], 0, v[136:137]
	global_load_dwordx4 v[188:191], v[136:137], off
	global_load_dwordx4 v[192:195], v[136:137], off offset:256
	v_add_u32_e32 v232, 16, v132
	v_add_u32_e32 v186, 32, v132
	v_add_u32_e32 v184, 48, v132
	v_add_u32_e32 v182, 0x80, v132
	v_add_u32_e32 v180, 0x90, v132
	v_add_u32_e32 v178, 0xa0, v132
	v_add_u32_e32 v176, 0xb0, v132
	v_ashrrev_i32_e32 v233, 31, v232
	v_ashrrev_i32_e32 v187, 31, v186
	v_ashrrev_i32_e32 v185, 31, v184
	v_ashrrev_i32_e32 v183, 31, v182
	v_ashrrev_i32_e32 v181, 31, v180
	v_ashrrev_i32_e32 v179, 31, v178
	v_ashrrev_i32_e32 v177, 31, v176
	v_lshlrev_b64 v[234:235], 11, v[132:133]
	v_lshlrev_b64 v[132:133], 12, v[232:233]
	v_lshlrev_b64 v[136:137], 12, v[186:187]
	v_lshlrev_b64 v[138:139], 12, v[184:185]
	v_lshlrev_b64 v[140:141], 12, v[182:183]
	v_lshlrev_b64 v[142:143], 12, v[180:181]
	v_lshlrev_b64 v[144:145], 12, v[178:179]
	v_lshlrev_b64 v[146:147], 12, v[176:177]
	v_lshl_add_u64 v[132:133], v[134:135], 0, v[132:133]
	v_lshl_add_u64 v[136:137], v[134:135], 0, v[136:137]
	v_lshl_add_u64 v[138:139], v[134:135], 0, v[138:139]
	v_lshl_add_u64 v[140:141], v[134:135], 0, v[140:141]
	v_lshl_add_u64 v[142:143], v[134:135], 0, v[142:143]
	v_lshl_add_u64 v[236:237], v[134:135], 0, v[144:145]
	v_lshl_add_u64 v[134:135], v[134:135], 0, v[146:147]
	global_load_dwordx4 v[214:217], v[132:133], off
	global_load_dwordx4 v[218:221], v[132:133], off offset:256
	global_load_dwordx4 v[226:229], v[136:137], off
	global_load_dwordx4 v[172:175], v[136:137], off offset:256
	global_load_dwordx4 v[168:171], v[138:139], off
	global_load_dwordx4 v[164:167], v[138:139], off offset:256
	global_load_dwordx4 v[160:163], v[140:141], off
	global_load_dwordx4 v[156:159], v[140:141], off offset:256
	global_load_dwordx4 v[152:155], v[142:143], off
	global_load_dwordx4 v[148:151], v[142:143], off offset:256
	global_load_dwordx4 v[144:147], v[236:237], off
	s_nop 0
	global_load_dwordx4 v[140:143], v[236:237], off offset:256
	global_load_dwordx4 v[136:139], v[134:135], off
	s_nop 0
	global_load_dwordx4 v[132:135], v[134:135], off offset:256
	s_mov_b32 s25, s14
	s_mov_b32 s24, s16
	s_mov_b64 s[26:27], s[20:21]
	s_mov_b64 s[22:23], s[18:19]
	s_waitcnt vmcnt(15)
	v_lshlrev_b32_e32 v1, 16, v188
	v_and_b32_e32 v188, 0xffff0000, v188
	v_lshlrev_b32_e32 v196, 16, v189
	v_and_b32_e32 v189, 0xffff0000, v189
	v_lshlrev_b32_e32 v225, 16, v190
	v_max_f32_e32 v1, v1, v1
	v_max_f32_e32 v188, v188, v188
	v_max_f32_e32 v196, v196, v196
	v_max_f32_e32 v189, v189, v189
	v_max_f32_e32 v225, v225, v225
	v_max_f32_e32 v1, 0x219392ef, v1
	v_max_f32_e32 v188, 0x219392ef, v188
	v_max_f32_e32 v196, 0x219392ef, v196
	v_max_f32_e32 v189, 0x219392ef, v189
	v_max_f32_e32 v225, 0x219392ef, v225
	v_mul_f32_e32 v1, v128, v1
	v_mul_f32_e32 v128, v129, v188
	v_mul_f32_e32 v129, v130, v196
	v_mul_f32_e32 v130, v131, v189
	v_mul_f32_e32 v131, v124, v225
	v_cvt_pk_bf16_f32 v124, v1, v128
	s_waitcnt vmcnt(14)
	v_lshlrev_b32_e32 v1, 16, v192
	v_max_f32_e32 v1, v1, v1
	v_max_f32_e32 v1, 0x219392ef, v1
	v_and_b32_e32 v190, 0xffff0000, v190
	v_lshlrev_b32_e32 v230, 16, v191
	v_and_b32_e32 v191, 0xffff0000, v191
	v_mul_f32_e32 v1, v120, v1
	v_and_b32_e32 v120, 0xffff0000, v192
	v_max_f32_e32 v190, v190, v190
	v_max_f32_e32 v191, v191, v191
	v_max_f32_e32 v120, v120, v120
	v_max_f32_e32 v230, v230, v230
	v_max_f32_e32 v190, 0x219392ef, v190
	v_max_f32_e32 v191, 0x219392ef, v191
	v_max_f32_e32 v120, 0x219392ef, v120
	v_max_f32_e32 v230, 0x219392ef, v230
	v_mul_f32_e32 v188, v125, v190
	v_mul_f32_e32 v127, v127, v191
	v_cvt_pk_bf16_f32 v125, v129, v130
	v_lshl_add_u64 v[128:129], s[78:79], 0, v[234:235]
	v_mul_f32_e32 v120, v121, v120
	v_mul_f32_e32 v189, v126, v230
	v_cvt_pk_bf16_f32 v126, v131, v188
	v_cvt_pk_bf16_f32 v127, v189, v127
	v_lshl_add_u64 v[128:129], v[128:129], 0, v[2:3]
	global_store_dwordx4 v[128:129], v[124:127], off
	s_nop 1
	v_cvt_pk_bf16_f32 v120, v1, v120
	v_lshlrev_b32_e32 v1, 16, v193
	v_and_b32_e32 v121, 0xffff0000, v193
	v_max_f32_e32 v1, v1, v1
	v_max_f32_e32 v121, v121, v121
	v_max_f32_e32 v1, 0x219392ef, v1
	v_max_f32_e32 v121, 0x219392ef, v121
	v_mul_f32_e32 v1, v122, v1
	v_mul_f32_e32 v121, v123, v121
	v_cvt_pk_bf16_f32 v121, v1, v121
	v_lshlrev_b32_e32 v1, 16, v194
	v_max_f32_e32 v1, v1, v1
	v_max_f32_e32 v1, 0x219392ef, v1
	v_mul_f32_e32 v1, v116, v1
	v_and_b32_e32 v116, 0xffff0000, v194
	v_max_f32_e32 v116, v116, v116
	v_max_f32_e32 v116, 0x219392ef, v116
	v_mul_f32_e32 v116, v117, v116
	v_cvt_pk_bf16_f32 v122, v1, v116
	v_lshlrev_b32_e32 v1, 16, v195
	v_max_f32_e32 v1, v1, v1
	v_and_b32_e32 v116, 0xffff0000, v195
	v_max_f32_e32 v1, 0x219392ef, v1
	v_max_f32_e32 v116, v116, v116
	v_mul_f32_e32 v1, v118, v1
	v_max_f32_e32 v116, 0x219392ef, v116
	v_mul_f32_e32 v116, v119, v116
	v_cvt_pk_bf16_f32 v123, v1, v116
	s_waitcnt vmcnt(14)
	v_lshlrev_b32_e32 v1, 16, v214
	v_max_f32_e32 v1, v1, v1
	v_max_f32_e32 v1, 0x219392ef, v1
	v_mul_f32_e32 v1, v112, v1
	v_and_b32_e32 v112, 0xffff0000, v214
	v_max_f32_e32 v112, v112, v112
	v_max_f32_e32 v112, 0x219392ef, v112
	v_mul_f32_e32 v112, v113, v112
	v_lshl_add_u64 v[116:117], v[128:129], 0, s[6:7]
	global_store_dwordx4 v[116:117], v[120:123], off
	s_nop 1
	v_cvt_pk_bf16_f32 v112, v1, v112
	v_lshlrev_b32_e32 v1, 16, v215
	v_and_b32_e32 v113, 0xffff0000, v215
	v_max_f32_e32 v1, v1, v1
	v_max_f32_e32 v113, v113, v113
	v_max_f32_e32 v1, 0x219392ef, v1
	v_max_f32_e32 v113, 0x219392ef, v113
	v_mul_f32_e32 v1, v114, v1
	v_mul_f32_e32 v113, v115, v113
	v_cvt_pk_bf16_f32 v113, v1, v113
	v_lshlrev_b32_e32 v1, 16, v216
	v_max_f32_e32 v1, v1, v1
	v_max_f32_e32 v1, 0x219392ef, v1
	v_mul_f32_e32 v1, v108, v1
	v_and_b32_e32 v108, 0xffff0000, v216
	v_max_f32_e32 v108, v108, v108
	v_max_f32_e32 v108, 0x219392ef, v108
	v_mul_f32_e32 v108, v109, v108
	v_cvt_pk_bf16_f32 v114, v1, v108
	v_lshlrev_b32_e32 v1, 16, v217
	v_max_f32_e32 v1, v1, v1
	v_and_b32_e32 v108, 0xffff0000, v217
	v_max_f32_e32 v1, 0x219392ef, v1
	v_max_f32_e32 v108, v108, v108
	v_mul_f32_e32 v1, v110, v1
	v_max_f32_e32 v108, 0x219392ef, v108
	v_mul_f32_e32 v108, v111, v108
	v_cvt_pk_bf16_f32 v115, v1, v108
	s_waitcnt vmcnt(14)
	v_lshlrev_b32_e32 v1, 16, v218
	v_max_f32_e32 v1, v1, v1
	v_max_f32_e32 v1, 0x219392ef, v1
	v_mul_f32_e32 v1, v104, v1
	v_and_b32_e32 v104, 0xffff0000, v218
	v_max_f32_e32 v104, v104, v104
	v_lshlrev_b64 v[108:109], 11, v[232:233]
	v_max_f32_e32 v104, 0x219392ef, v104
	v_lshl_add_u64 v[108:109], s[78:79], 0, v[108:109]
	v_mul_f32_e32 v104, v105, v104
	v_lshl_add_u64 v[108:109], v[108:109], 0, v[2:3]
	global_store_dwordx4 v[108:109], v[112:115], off
	s_nop 1
	v_cvt_pk_bf16_f32 v104, v1, v104
	v_lshlrev_b32_e32 v1, 16, v219
	v_and_b32_e32 v105, 0xffff0000, v219
	v_max_f32_e32 v1, v1, v1
	v_max_f32_e32 v105, v105, v105
	v_max_f32_e32 v1, 0x219392ef, v1
	v_max_f32_e32 v105, 0x219392ef, v105
	v_mul_f32_e32 v1, v106, v1
	v_mul_f32_e32 v105, v107, v105
	v_cvt_pk_bf16_f32 v105, v1, v105
	v_lshlrev_b32_e32 v1, 16, v220
	v_max_f32_e32 v1, v1, v1
	v_max_f32_e32 v1, 0x219392ef, v1
	v_mul_f32_e32 v1, v100, v1
	v_and_b32_e32 v100, 0xffff0000, v220
	v_max_f32_e32 v100, v100, v100
	v_max_f32_e32 v100, 0x219392ef, v100
	v_mul_f32_e32 v100, v101, v100
	v_cvt_pk_bf16_f32 v106, v1, v100
	v_lshlrev_b32_e32 v1, 16, v221
	v_max_f32_e32 v1, v1, v1
	v_and_b32_e32 v100, 0xffff0000, v221
	v_max_f32_e32 v1, 0x219392ef, v1
	v_max_f32_e32 v100, v100, v100
	v_mul_f32_e32 v1, v102, v1
	v_max_f32_e32 v100, 0x219392ef, v100
	v_mul_f32_e32 v100, v103, v100
	v_cvt_pk_bf16_f32 v107, v1, v100
	s_waitcnt vmcnt(14)
	v_lshlrev_b32_e32 v1, 16, v226
	v_max_f32_e32 v1, v1, v1
	v_max_f32_e32 v1, 0x219392ef, v1
	v_mul_f32_e32 v1, v96, v1
	v_and_b32_e32 v96, 0xffff0000, v226
	v_max_f32_e32 v96, v96, v96
	v_max_f32_e32 v96, 0x219392ef, v96
	v_mul_f32_e32 v96, v97, v96
	v_lshl_add_u64 v[100:101], v[108:109], 0, s[6:7]
	global_store_dwordx4 v[100:101], v[104:107], off
	s_nop 1
	v_cvt_pk_bf16_f32 v96, v1, v96
	v_lshlrev_b32_e32 v1, 16, v227
	v_and_b32_e32 v97, 0xffff0000, v227
	v_max_f32_e32 v1, v1, v1
	v_max_f32_e32 v97, v97, v97
	v_max_f32_e32 v1, 0x219392ef, v1
	v_max_f32_e32 v97, 0x219392ef, v97
	v_mul_f32_e32 v1, v98, v1
	v_mul_f32_e32 v97, v99, v97
	v_cvt_pk_bf16_f32 v97, v1, v97
	v_lshlrev_b32_e32 v1, 16, v228
	v_max_f32_e32 v1, v1, v1
	v_max_f32_e32 v1, 0x219392ef, v1
	v_mul_f32_e32 v1, v92, v1
	v_and_b32_e32 v92, 0xffff0000, v228
	v_max_f32_e32 v92, v92, v92
	v_max_f32_e32 v92, 0x219392ef, v92
	v_mul_f32_e32 v92, v93, v92
	v_cvt_pk_bf16_f32 v98, v1, v92
	v_lshlrev_b32_e32 v1, 16, v229
	v_max_f32_e32 v1, v1, v1
	v_and_b32_e32 v92, 0xffff0000, v229
	v_max_f32_e32 v1, 0x219392ef, v1
	v_max_f32_e32 v92, v92, v92
	v_mul_f32_e32 v1, v94, v1
	v_max_f32_e32 v92, 0x219392ef, v92
	v_mul_f32_e32 v92, v95, v92
	v_cvt_pk_bf16_f32 v99, v1, v92
	s_waitcnt vmcnt(14)
	v_lshlrev_b32_e32 v1, 16, v172
	v_max_f32_e32 v1, v1, v1
	v_max_f32_e32 v1, 0x219392ef, v1
	v_mul_f32_e32 v1, v88, v1
	v_and_b32_e32 v88, 0xffff0000, v172
	v_max_f32_e32 v88, v88, v88
	v_lshlrev_b64 v[92:93], 11, v[186:187]
	v_max_f32_e32 v88, 0x219392ef, v88
	v_lshl_add_u64 v[92:93], s[78:79], 0, v[92:93]
	v_mul_f32_e32 v88, v89, v88
	v_lshl_add_u64 v[92:93], v[92:93], 0, v[2:3]
	global_store_dwordx4 v[92:93], v[96:99], off
	s_nop 1
	v_cvt_pk_bf16_f32 v88, v1, v88
	v_lshlrev_b32_e32 v1, 16, v173
	v_and_b32_e32 v89, 0xffff0000, v173
	v_max_f32_e32 v1, v1, v1
	v_max_f32_e32 v89, v89, v89
	v_max_f32_e32 v1, 0x219392ef, v1
	v_max_f32_e32 v89, 0x219392ef, v89
	v_mul_f32_e32 v1, v90, v1
	v_mul_f32_e32 v89, v91, v89
	v_cvt_pk_bf16_f32 v89, v1, v89
	v_lshlrev_b32_e32 v1, 16, v174
	v_max_f32_e32 v1, v1, v1
	v_max_f32_e32 v1, 0x219392ef, v1
	v_mul_f32_e32 v1, v84, v1
	v_and_b32_e32 v84, 0xffff0000, v174
	v_max_f32_e32 v84, v84, v84
	v_max_f32_e32 v84, 0x219392ef, v84
	v_mul_f32_e32 v84, v85, v84
	v_cvt_pk_bf16_f32 v90, v1, v84
	v_lshlrev_b32_e32 v1, 16, v175
	v_max_f32_e32 v1, v1, v1
	v_and_b32_e32 v84, 0xffff0000, v175
	v_max_f32_e32 v1, 0x219392ef, v1
	v_max_f32_e32 v84, v84, v84
	v_mul_f32_e32 v1, v86, v1
	v_max_f32_e32 v84, 0x219392ef, v84
	v_mul_f32_e32 v84, v87, v84
	v_cvt_pk_bf16_f32 v91, v1, v84
	s_waitcnt vmcnt(14)
	v_lshlrev_b32_e32 v1, 16, v168
	v_max_f32_e32 v1, v1, v1
	v_max_f32_e32 v1, 0x219392ef, v1
	v_mul_f32_e32 v1, v80, v1
	v_and_b32_e32 v80, 0xffff0000, v168
	v_max_f32_e32 v80, v80, v80
	v_max_f32_e32 v80, 0x219392ef, v80
	v_mul_f32_e32 v80, v81, v80
	v_lshl_add_u64 v[84:85], v[92:93], 0, s[6:7]
	global_store_dwordx4 v[84:85], v[88:91], off
	s_nop 1
	v_cvt_pk_bf16_f32 v80, v1, v80
	v_lshlrev_b32_e32 v1, 16, v169
	v_and_b32_e32 v81, 0xffff0000, v169
	v_max_f32_e32 v1, v1, v1
	v_max_f32_e32 v81, v81, v81
	v_max_f32_e32 v1, 0x219392ef, v1
	v_max_f32_e32 v81, 0x219392ef, v81
	v_mul_f32_e32 v1, v82, v1
	v_mul_f32_e32 v81, v83, v81
	v_cvt_pk_bf16_f32 v81, v1, v81
	v_lshlrev_b32_e32 v1, 16, v170
	v_max_f32_e32 v1, v1, v1
	v_max_f32_e32 v1, 0x219392ef, v1
	v_mul_f32_e32 v1, v76, v1
	v_and_b32_e32 v76, 0xffff0000, v170
	v_max_f32_e32 v76, v76, v76
	v_max_f32_e32 v76, 0x219392ef, v76
	v_mul_f32_e32 v76, v77, v76
	v_cvt_pk_bf16_f32 v82, v1, v76
	v_lshlrev_b32_e32 v1, 16, v171
	v_max_f32_e32 v1, v1, v1
	v_and_b32_e32 v76, 0xffff0000, v171
	v_max_f32_e32 v1, 0x219392ef, v1
	v_max_f32_e32 v76, v76, v76
	v_mul_f32_e32 v1, v78, v1
	v_max_f32_e32 v76, 0x219392ef, v76
	v_mul_f32_e32 v76, v79, v76
	v_cvt_pk_bf16_f32 v83, v1, v76
	s_waitcnt vmcnt(14)
	v_lshlrev_b32_e32 v1, 16, v164
	v_max_f32_e32 v1, v1, v1
	v_max_f32_e32 v1, 0x219392ef, v1
	v_mul_f32_e32 v1, v72, v1
	v_and_b32_e32 v72, 0xffff0000, v164
	v_max_f32_e32 v72, v72, v72
	v_lshlrev_b64 v[76:77], 11, v[184:185]
	v_max_f32_e32 v72, 0x219392ef, v72
	v_lshl_add_u64 v[76:77], s[78:79], 0, v[76:77]
	v_mul_f32_e32 v72, v73, v72
	v_lshl_add_u64 v[76:77], v[76:77], 0, v[2:3]
	global_store_dwordx4 v[76:77], v[80:83], off
	s_nop 1
	v_cvt_pk_bf16_f32 v72, v1, v72
	v_lshlrev_b32_e32 v1, 16, v165
	v_and_b32_e32 v73, 0xffff0000, v165
	v_max_f32_e32 v1, v1, v1
	v_max_f32_e32 v73, v73, v73
	v_max_f32_e32 v1, 0x219392ef, v1
	v_max_f32_e32 v73, 0x219392ef, v73
	v_mul_f32_e32 v1, v74, v1
	v_mul_f32_e32 v73, v75, v73
	v_cvt_pk_bf16_f32 v73, v1, v73
	v_lshlrev_b32_e32 v1, 16, v166
	v_max_f32_e32 v1, v1, v1
	v_max_f32_e32 v1, 0x219392ef, v1
	v_mul_f32_e32 v1, v68, v1
	v_and_b32_e32 v68, 0xffff0000, v166
	v_max_f32_e32 v68, v68, v68
	v_max_f32_e32 v68, 0x219392ef, v68
	v_mul_f32_e32 v68, v69, v68
	v_cvt_pk_bf16_f32 v74, v1, v68
	v_lshlrev_b32_e32 v1, 16, v167
	v_max_f32_e32 v1, v1, v1
	v_and_b32_e32 v68, 0xffff0000, v167
	v_max_f32_e32 v1, 0x219392ef, v1
	v_max_f32_e32 v68, v68, v68
	v_mul_f32_e32 v1, v70, v1
	v_max_f32_e32 v68, 0x219392ef, v68
	v_mul_f32_e32 v68, v71, v68
	v_cvt_pk_bf16_f32 v75, v1, v68
	s_waitcnt vmcnt(14)
	v_lshlrev_b32_e32 v1, 16, v160
	v_max_f32_e32 v1, v1, v1
	v_max_f32_e32 v1, 0x219392ef, v1
	v_mul_f32_e32 v1, v64, v1
	v_and_b32_e32 v64, 0xffff0000, v160
	v_max_f32_e32 v64, v64, v64
	v_max_f32_e32 v64, 0x219392ef, v64
	v_mul_f32_e32 v64, v65, v64
	v_lshl_add_u64 v[68:69], v[76:77], 0, s[6:7]
	global_store_dwordx4 v[68:69], v[72:75], off
	s_nop 1
	v_cvt_pk_bf16_f32 v64, v1, v64
	v_lshlrev_b32_e32 v1, 16, v161
	v_and_b32_e32 v65, 0xffff0000, v161
	v_max_f32_e32 v1, v1, v1
	v_max_f32_e32 v65, v65, v65
	v_max_f32_e32 v1, 0x219392ef, v1
	v_max_f32_e32 v65, 0x219392ef, v65
	v_mul_f32_e32 v1, v66, v1
	v_mul_f32_e32 v65, v67, v65
	v_cvt_pk_bf16_f32 v65, v1, v65
	v_lshlrev_b32_e32 v1, 16, v162
	v_max_f32_e32 v1, v1, v1
	v_max_f32_e32 v1, 0x219392ef, v1
	v_mul_f32_e32 v1, v60, v1
	v_and_b32_e32 v60, 0xffff0000, v162
	v_max_f32_e32 v60, v60, v60
	v_max_f32_e32 v60, 0x219392ef, v60
	v_mul_f32_e32 v60, v61, v60
	v_cvt_pk_bf16_f32 v66, v1, v60
	v_lshlrev_b32_e32 v1, 16, v163
	v_max_f32_e32 v1, v1, v1
	v_and_b32_e32 v60, 0xffff0000, v163
	v_max_f32_e32 v1, 0x219392ef, v1
	v_max_f32_e32 v60, v60, v60
	v_mul_f32_e32 v1, v62, v1
	v_max_f32_e32 v60, 0x219392ef, v60
	v_mul_f32_e32 v60, v63, v60
	v_cvt_pk_bf16_f32 v67, v1, v60
	s_waitcnt vmcnt(14)
	v_lshlrev_b32_e32 v1, 16, v156
	v_max_f32_e32 v1, v1, v1
	v_max_f32_e32 v1, 0x219392ef, v1
	v_mul_f32_e32 v1, v56, v1
	v_and_b32_e32 v56, 0xffff0000, v156
	v_max_f32_e32 v56, v56, v56
	v_lshlrev_b64 v[60:61], 11, v[182:183]
	v_max_f32_e32 v56, 0x219392ef, v56
	v_lshl_add_u64 v[60:61], s[78:79], 0, v[60:61]
	v_mul_f32_e32 v56, v57, v56
	v_lshl_add_u64 v[60:61], v[60:61], 0, v[2:3]
	global_store_dwordx4 v[60:61], v[64:67], off
	s_nop 1
	v_cvt_pk_bf16_f32 v56, v1, v56
	v_lshlrev_b32_e32 v1, 16, v157
	v_and_b32_e32 v57, 0xffff0000, v157
	v_max_f32_e32 v1, v1, v1
	v_max_f32_e32 v57, v57, v57
	v_max_f32_e32 v1, 0x219392ef, v1
	v_max_f32_e32 v57, 0x219392ef, v57
	v_mul_f32_e32 v1, v58, v1
	v_mul_f32_e32 v57, v59, v57
	v_cvt_pk_bf16_f32 v57, v1, v57
	v_lshlrev_b32_e32 v1, 16, v158
	v_max_f32_e32 v1, v1, v1
	v_max_f32_e32 v1, 0x219392ef, v1
	v_mul_f32_e32 v1, v52, v1
	v_and_b32_e32 v52, 0xffff0000, v158
	v_max_f32_e32 v52, v52, v52
	v_max_f32_e32 v52, 0x219392ef, v52
	v_mul_f32_e32 v52, v53, v52
	v_cvt_pk_bf16_f32 v58, v1, v52
	v_lshlrev_b32_e32 v1, 16, v159
	v_max_f32_e32 v1, v1, v1
	v_and_b32_e32 v52, 0xffff0000, v159
	v_max_f32_e32 v1, 0x219392ef, v1
	v_max_f32_e32 v52, v52, v52
	v_mul_f32_e32 v1, v54, v1
	v_max_f32_e32 v52, 0x219392ef, v52
	v_mul_f32_e32 v52, v55, v52
	v_cvt_pk_bf16_f32 v59, v1, v52
	s_waitcnt vmcnt(14)
	v_lshlrev_b32_e32 v1, 16, v152
	v_max_f32_e32 v1, v1, v1
	v_max_f32_e32 v1, 0x219392ef, v1
	v_mul_f32_e32 v1, v48, v1
	v_and_b32_e32 v48, 0xffff0000, v152
	v_max_f32_e32 v48, v48, v48
	v_max_f32_e32 v48, 0x219392ef, v48
	v_mul_f32_e32 v48, v49, v48
	v_lshl_add_u64 v[52:53], v[60:61], 0, s[6:7]
	global_store_dwordx4 v[52:53], v[56:59], off
	s_nop 1
	v_cvt_pk_bf16_f32 v48, v1, v48
	v_lshlrev_b32_e32 v1, 16, v153
	v_and_b32_e32 v49, 0xffff0000, v153
	v_max_f32_e32 v1, v1, v1
	v_max_f32_e32 v49, v49, v49
	v_max_f32_e32 v1, 0x219392ef, v1
	v_max_f32_e32 v49, 0x219392ef, v49
	v_mul_f32_e32 v1, v50, v1
	v_mul_f32_e32 v49, v51, v49
	v_cvt_pk_bf16_f32 v49, v1, v49
	v_lshlrev_b32_e32 v1, 16, v154
	v_max_f32_e32 v1, v1, v1
	v_max_f32_e32 v1, 0x219392ef, v1
	v_mul_f32_e32 v1, v44, v1
	v_and_b32_e32 v44, 0xffff0000, v154
	v_max_f32_e32 v44, v44, v44
	v_max_f32_e32 v44, 0x219392ef, v44
	v_mul_f32_e32 v44, v45, v44
	v_cvt_pk_bf16_f32 v50, v1, v44
	v_lshlrev_b32_e32 v1, 16, v155
	v_max_f32_e32 v1, v1, v1
	v_and_b32_e32 v44, 0xffff0000, v155
	v_max_f32_e32 v1, 0x219392ef, v1
	v_max_f32_e32 v44, v44, v44
	v_mul_f32_e32 v1, v46, v1
	v_max_f32_e32 v44, 0x219392ef, v44
	v_mul_f32_e32 v44, v47, v44
	v_cvt_pk_bf16_f32 v51, v1, v44
	s_waitcnt vmcnt(14)
	v_lshlrev_b32_e32 v1, 16, v148
	v_max_f32_e32 v1, v1, v1
	v_max_f32_e32 v1, 0x219392ef, v1
	v_mul_f32_e32 v1, v40, v1
	v_and_b32_e32 v40, 0xffff0000, v148
	v_max_f32_e32 v40, v40, v40
	v_lshlrev_b64 v[44:45], 11, v[180:181]
	v_max_f32_e32 v40, 0x219392ef, v40
	v_lshl_add_u64 v[44:45], s[78:79], 0, v[44:45]
	v_mul_f32_e32 v40, v41, v40
	v_lshl_add_u64 v[44:45], v[44:45], 0, v[2:3]
	global_store_dwordx4 v[44:45], v[48:51], off
	s_nop 1
	v_cvt_pk_bf16_f32 v40, v1, v40
	v_lshlrev_b32_e32 v1, 16, v149
	v_and_b32_e32 v41, 0xffff0000, v149
	v_max_f32_e32 v1, v1, v1
	v_max_f32_e32 v41, v41, v41
	v_max_f32_e32 v1, 0x219392ef, v1
	v_max_f32_e32 v41, 0x219392ef, v41
	v_mul_f32_e32 v1, v42, v1
	v_mul_f32_e32 v41, v43, v41
	v_cvt_pk_bf16_f32 v41, v1, v41
	v_lshlrev_b32_e32 v1, 16, v150
	v_max_f32_e32 v1, v1, v1
	v_max_f32_e32 v1, 0x219392ef, v1
	v_mul_f32_e32 v1, v36, v1
	v_and_b32_e32 v36, 0xffff0000, v150
	v_max_f32_e32 v36, v36, v36
	v_max_f32_e32 v36, 0x219392ef, v36
	v_mul_f32_e32 v36, v37, v36
	v_cvt_pk_bf16_f32 v42, v1, v36
	v_lshlrev_b32_e32 v1, 16, v151
	v_max_f32_e32 v1, v1, v1
	v_and_b32_e32 v36, 0xffff0000, v151
	v_max_f32_e32 v1, 0x219392ef, v1
	v_max_f32_e32 v36, v36, v36
	v_mul_f32_e32 v1, v38, v1
	v_max_f32_e32 v36, 0x219392ef, v36
	v_mul_f32_e32 v36, v39, v36
	v_cvt_pk_bf16_f32 v43, v1, v36
	s_waitcnt vmcnt(14)
	v_lshlrev_b32_e32 v1, 16, v144
	v_max_f32_e32 v1, v1, v1
	v_max_f32_e32 v1, 0x219392ef, v1
	v_mul_f32_e32 v1, v32, v1
	v_and_b32_e32 v32, 0xffff0000, v144
	v_max_f32_e32 v32, v32, v32
	v_max_f32_e32 v32, 0x219392ef, v32
	v_mul_f32_e32 v32, v33, v32
	v_lshl_add_u64 v[36:37], v[44:45], 0, s[6:7]
	global_store_dwordx4 v[36:37], v[40:43], off
	s_nop 1
	v_cvt_pk_bf16_f32 v32, v1, v32
	v_lshlrev_b32_e32 v1, 16, v145
	v_and_b32_e32 v33, 0xffff0000, v145
	v_max_f32_e32 v1, v1, v1
	v_max_f32_e32 v33, v33, v33
	v_max_f32_e32 v1, 0x219392ef, v1
	v_max_f32_e32 v33, 0x219392ef, v33
	v_mul_f32_e32 v1, v34, v1
	v_mul_f32_e32 v33, v35, v33
	v_cvt_pk_bf16_f32 v33, v1, v33
	v_lshlrev_b32_e32 v1, 16, v146
	v_max_f32_e32 v1, v1, v1
	v_max_f32_e32 v1, 0x219392ef, v1
	v_mul_f32_e32 v1, v28, v1
	v_and_b32_e32 v28, 0xffff0000, v146
	v_max_f32_e32 v28, v28, v28
	v_max_f32_e32 v28, 0x219392ef, v28
	v_mul_f32_e32 v28, v29, v28
	v_cvt_pk_bf16_f32 v34, v1, v28
	v_lshlrev_b32_e32 v1, 16, v147
	v_max_f32_e32 v1, v1, v1
	v_and_b32_e32 v28, 0xffff0000, v147
	v_max_f32_e32 v1, 0x219392ef, v1
	v_max_f32_e32 v28, v28, v28
	v_mul_f32_e32 v1, v30, v1
	v_max_f32_e32 v28, 0x219392ef, v28
	v_mul_f32_e32 v28, v31, v28
	v_cvt_pk_bf16_f32 v35, v1, v28
	s_waitcnt vmcnt(14)
	v_lshlrev_b32_e32 v1, 16, v140
	v_max_f32_e32 v1, v1, v1
	v_max_f32_e32 v1, 0x219392ef, v1
	v_mul_f32_e32 v1, v24, v1
	v_and_b32_e32 v24, 0xffff0000, v140
	v_max_f32_e32 v24, v24, v24
	v_lshlrev_b64 v[28:29], 11, v[178:179]
	v_max_f32_e32 v24, 0x219392ef, v24
	v_lshl_add_u64 v[28:29], s[78:79], 0, v[28:29]
	v_mul_f32_e32 v24, v25, v24
	v_lshl_add_u64 v[28:29], v[28:29], 0, v[2:3]
	global_store_dwordx4 v[28:29], v[32:35], off
	s_nop 1
	v_cvt_pk_bf16_f32 v24, v1, v24
	v_lshlrev_b32_e32 v1, 16, v141
	v_and_b32_e32 v25, 0xffff0000, v141
	v_max_f32_e32 v1, v1, v1
	v_max_f32_e32 v25, v25, v25
	v_max_f32_e32 v1, 0x219392ef, v1
	v_max_f32_e32 v25, 0x219392ef, v25
	v_mul_f32_e32 v1, v26, v1
	v_mul_f32_e32 v25, v27, v25
	v_cvt_pk_bf16_f32 v25, v1, v25
	v_lshlrev_b32_e32 v1, 16, v142
	v_max_f32_e32 v1, v1, v1
	v_max_f32_e32 v1, 0x219392ef, v1
	v_mul_f32_e32 v1, v20, v1
	v_and_b32_e32 v20, 0xffff0000, v142
	v_max_f32_e32 v20, v20, v20
	v_max_f32_e32 v20, 0x219392ef, v20
	v_mul_f32_e32 v20, v21, v20
	v_cvt_pk_bf16_f32 v26, v1, v20
	v_lshlrev_b32_e32 v1, 16, v143
	v_max_f32_e32 v1, v1, v1
	v_and_b32_e32 v20, 0xffff0000, v143
	v_max_f32_e32 v1, 0x219392ef, v1
	v_max_f32_e32 v20, v20, v20
	v_mul_f32_e32 v1, v22, v1
	v_max_f32_e32 v20, 0x219392ef, v20
	v_mul_f32_e32 v20, v23, v20
	v_cvt_pk_bf16_f32 v27, v1, v20
	s_waitcnt vmcnt(14)
	v_lshlrev_b32_e32 v1, 16, v136
	v_max_f32_e32 v1, v1, v1
	v_max_f32_e32 v1, 0x219392ef, v1
	v_mul_f32_e32 v1, v16, v1
	v_and_b32_e32 v16, 0xffff0000, v136
	v_max_f32_e32 v16, v16, v16
	v_max_f32_e32 v16, 0x219392ef, v16
	v_mul_f32_e32 v16, v17, v16
	v_lshl_add_u64 v[20:21], v[28:29], 0, s[6:7]
	global_store_dwordx4 v[20:21], v[24:27], off
	s_nop 1
	v_cvt_pk_bf16_f32 v16, v1, v16
	v_lshlrev_b32_e32 v1, 16, v137
	v_and_b32_e32 v17, 0xffff0000, v137
	v_max_f32_e32 v1, v1, v1
	v_max_f32_e32 v17, v17, v17
	v_max_f32_e32 v1, 0x219392ef, v1
	v_max_f32_e32 v17, 0x219392ef, v17
	v_mul_f32_e32 v1, v18, v1
	v_mul_f32_e32 v17, v19, v17
	v_cvt_pk_bf16_f32 v17, v1, v17
	v_lshlrev_b32_e32 v1, 16, v138
	v_max_f32_e32 v1, v1, v1
	v_max_f32_e32 v1, 0x219392ef, v1
	v_mul_f32_e32 v1, v12, v1
	v_and_b32_e32 v12, 0xffff0000, v138
	v_max_f32_e32 v12, v12, v12
	v_max_f32_e32 v12, 0x219392ef, v12
	v_mul_f32_e32 v12, v13, v12
	v_cvt_pk_bf16_f32 v18, v1, v12
	v_and_b32_e32 v12, 0xffff0000, v139
	v_lshlrev_b32_e32 v1, 16, v139
	v_max_f32_e32 v12, v12, v12
	v_max_f32_e32 v1, v1, v1
	v_max_f32_e32 v12, 0x219392ef, v12
	v_max_f32_e32 v1, 0x219392ef, v1
	v_mul_f32_e32 v12, v15, v12
	v_mul_f32_e32 v1, v14, v1
	v_cvt_pk_bf16_f32 v19, v1, v12
	v_lshlrev_b64 v[12:13], 11, v[176:177]
	v_lshl_add_u64 v[12:13], s[78:79], 0, v[12:13]
	v_lshl_add_u64 v[12:13], v[12:13], 0, v[2:3]
	s_waitcnt vmcnt(14)
	v_lshlrev_b32_e32 v1, 16, v132
	v_and_b32_e32 v2, 0xffff0000, v132
	v_max_f32_e32 v1, v1, v1
	v_max_f32_e32 v2, v2, v2
	v_max_f32_e32 v1, 0x219392ef, v1
	v_max_f32_e32 v2, 0x219392ef, v2
	v_mul_f32_e32 v1, v8, v1
	v_mul_f32_e32 v2, v9, v2
	global_store_dwordx4 v[12:13], v[16:19], off
	s_nop 1
	v_cvt_pk_bf16_f32 v2, v1, v2
	v_lshlrev_b32_e32 v1, 16, v133
	v_and_b32_e32 v3, 0xffff0000, v133
	v_max_f32_e32 v1, v1, v1
	v_max_f32_e32 v3, v3, v3
	v_max_f32_e32 v1, 0x219392ef, v1
	v_max_f32_e32 v3, 0x219392ef, v3
	v_mul_f32_e32 v1, v10, v1
	v_mul_f32_e32 v3, v11, v3
	v_cvt_pk_bf16_f32 v3, v1, v3
	v_lshlrev_b32_e32 v1, 16, v134
	v_max_f32_e32 v1, v1, v1
	v_max_f32_e32 v1, 0x219392ef, v1
	v_mul_f32_e32 v1, v4, v1
	v_and_b32_e32 v4, 0xffff0000, v134
	v_max_f32_e32 v4, v4, v4
	v_max_f32_e32 v4, 0x219392ef, v4
	v_mul_f32_e32 v4, v5, v4
	v_and_b32_e32 v5, 0xffff0000, v135
	v_cvt_pk_bf16_f32 v4, v1, v4
	v_lshlrev_b32_e32 v1, 16, v135
	v_max_f32_e32 v5, v5, v5
	v_max_f32_e32 v1, v1, v1
	v_max_f32_e32 v5, 0x219392ef, v5
	v_max_f32_e32 v1, 0x219392ef, v1
	v_mul_f32_e32 v5, v7, v5
	v_mul_f32_e32 v1, v6, v1
	v_cvt_pk_bf16_f32 v5, v1, v5
	v_lshl_add_u64 v[6:7], v[12:13], 0, s[6:7]
	global_store_dwordx4 v[6:7], v[2:5], off
	s_nop 1
	s_cbranch_vccnz .LBB0_538

.LBB0_536:
	s_cmpk_lg_i32 s24, 0x400
	s_cbranch_scc1 .LBB0_535
	v_mov_b32_e32 v1, v222
	v_mov_b32_e32 v2, v197
	s_nop 0
	v_add_u32_e32 v218, s15, v2
	v_lshl_add_u32 v2, v1, 3, s47
	v_ashrrev_i32_e32 v3, 31, v2
	v_ashrrev_i32_e32 v219, 31, v218
	v_lshl_add_u64 v[2:3], v[2:3], 1, s[74:75]
	v_lshlrev_b64 v[132:133], 12, v[218:219]
	v_lshl_add_u64 v[220:221], v[2:3], 0, v[132:133]
	global_load_dwordx4 v[172:175], v[220:221], off offset:2048
	global_load_dwordx4 v[176:179], v[220:221], off
	global_load_dwordx4 v[188:191], v[220:221], off offset:2304
	global_load_dwordx4 v[192:195], v[220:221], off offset:256
	v_lshl_add_u64 v[136:137], v[220:221], 0, s[8:9]
	v_add_co_u32_e32 v138, vcc, s37, v220
	v_add_u32_e32 v132, 32, v218
	s_nop 0
	v_addc_co_u32_e32 v139, vcc, 0, v221, vcc
	global_load_dwordx4 v[160:163], v[136:137], off offset:2048
	global_load_dwordx4 v[140:143], v[136:137], off offset:256
	global_load_dwordx4 v[156:159], v[138:139], off
	global_load_dwordx4 v[144:147], v[136:137], off offset:2304
	v_add_u32_e32 v134, 48, v218
	v_ashrrev_i32_e32 v133, 31, v132
	v_ashrrev_i32_e32 v135, 31, v134
	v_lshlrev_b64 v[132:133], 12, v[132:133]
	v_lshlrev_b64 v[134:135], 12, v[134:135]
	v_lshl_add_u64 v[132:133], v[2:3], 0, v[132:133]
	v_lshl_add_u64 v[226:227], v[2:3], 0, v[134:135]
	global_load_dwordx4 v[180:183], v[132:133], off
	global_load_dwordx4 v[164:167], v[132:133], off offset:256
	global_load_dwordx4 v[184:187], v[132:133], off offset:2048
	global_load_dwordx4 v[168:171], v[132:133], off offset:2304
	global_load_dwordx4 v[148:151], v[226:227], off
	s_nop 0
	global_load_dwordx4 v[132:135], v[226:227], off offset:256
	global_load_dwordx4 v[152:155], v[226:227], off offset:2048
	global_load_dwordx4 v[136:139], v[226:227], off offset:2304
	s_waitcnt vmcnt(15)
	v_lshlrev_b32_e32 v1, 16, v172
	v_and_b32_e32 v196, 0xffff0000, v172
	s_waitcnt vmcnt(14)
	v_lshlrev_b32_e32 v226, 16, v176
	v_and_b32_e32 v227, 0xffff0000, v176
	v_lshlrev_b32_e32 v219, 16, v173
	v_and_b32_e32 v225, 0xffff0000, v173
	v_lshlrev_b32_e32 v172, 16, v177
	v_and_b32_e32 v173, 0xffff0000, v177
	v_lshlrev_b32_e32 v176, 16, v178
	v_and_b32_e32 v177, 0xffff0000, v178
	v_lshlrev_b32_e32 v178, 16, v175
	v_and_b32_e32 v230, 0xffff0000, v175
	v_max_f32_e32 v178, v178, v178
	v_max_f32_e32 v230, v230, v230
	v_lshlrev_b32_e32 v228, 16, v174
	v_and_b32_e32 v229, 0xffff0000, v174
	v_lshlrev_b32_e32 v174, 16, v179
	v_and_b32_e32 v175, 0xffff0000, v179
	s_waitcnt vmcnt(13)
	v_lshlrev_b32_e32 v179, 16, v188
	v_and_b32_e32 v188, 0xffff0000, v188
	v_max_f32_e32 v1, v1, v1
	v_max_f32_e32 v234, 0x219392ef, v178
	v_max_f32_e32 v230, 0x219392ef, v230
	v_max_f32_e32 v188, v188, v188
	v_max_f32_e32 v1, 0x219392ef, v1
	v_rcp_f32_e32 v234, v234
	v_rcp_f32_e32 v235, v230
	v_rcp_f32_e32 v178, v1
	v_max_f32_e32 v1, 0x219392ef, v188
	v_max_f32_e32 v219, v219, v219
	v_max_f32_e32 v225, v225, v225
	v_rcp_f32_e32 v237, v1
	v_lshlrev_b32_e32 v1, 16, v189
	v_max_f32_e32 v228, v228, v228
	v_max_f32_e32 v229, v229, v229
	v_max_f32_e32 v219, 0x219392ef, v219
	v_max_f32_e32 v225, 0x219392ef, v225
	v_max_f32_e32 v1, v1, v1
	v_max_f32_e32 v179, v179, v179
	v_max_f32_e32 v232, 0x219392ef, v228
	v_max_f32_e32 v233, 0x219392ef, v229
	v_rcp_f32_e32 v228, v219
	v_rcp_f32_e32 v229, v225
	v_pk_mul_f32 v[174:175], v[234:235], v[174:175]
	v_max_f32_e32 v1, 0x219392ef, v1
	v_max_f32_e32 v236, 0x219392ef, v179
	v_pk_mul_f32 v[126:127], v[126:127], v[174:175]
	v_rcp_f32_e32 v174, v1
	v_and_b32_e32 v1, 0xffff0000, v189
	v_rcp_f32_e32 v236, v236
	v_max_f32_e32 v1, v1, v1
	v_max_f32_e32 v1, 0x219392ef, v1
	v_pk_mul_f32 v[172:173], v[228:229], v[172:173]
	v_rcp_f32_e32 v175, v1
	v_lshlrev_b32_e32 v1, 16, v190
	v_pk_mul_f32 v[130:131], v[130:131], v[172:173]
	s_waitcnt vmcnt(12)
	v_lshlrev_b32_e32 v172, 16, v192
	v_and_b32_e32 v173, 0xffff0000, v192
	v_max_f32_e32 v1, v1, v1
	v_pk_mul_f32 v[172:173], v[236:237], v[172:173]
	v_max_f32_e32 v1, 0x219392ef, v1
	v_rcp_f32_e32 v232, v232
	v_rcp_f32_e32 v233, v233
	v_pk_mul_f32 v[120:121], v[120:121], v[172:173]
	v_rcp_f32_e32 v172, v1
	v_and_b32_e32 v1, 0xffff0000, v190
	v_max_f32_e32 v1, v1, v1
	v_max_f32_e32 v1, 0x219392ef, v1
	v_rcp_f32_e32 v173, v1
	v_lshlrev_b32_e32 v1, 16, v191
	v_pk_mul_f32 v[176:177], v[232:233], v[176:177]
	v_max_f32_e32 v1, v1, v1
	v_pk_mul_f32 v[124:125], v[124:125], v[176:177]
	v_lshlrev_b32_e32 v176, 16, v193
	v_and_b32_e32 v177, 0xffff0000, v193
	v_max_f32_e32 v1, 0x219392ef, v1
	v_pk_mul_f32 v[174:175], v[174:175], v[176:177]
	v_rcp_f32_e32 v176, v1
	v_and_b32_e32 v1, 0xffff0000, v191
	v_max_f32_e32 v1, v1, v1
	v_max_f32_e32 v1, 0x219392ef, v1
	v_rcp_f32_e32 v177, v1
	s_waitcnt vmcnt(11)
	v_lshlrev_b32_e32 v1, 16, v160
	v_pk_mul_f32 v[122:123], v[122:123], v[174:175]
	v_lshlrev_b32_e32 v174, 16, v194
	v_and_b32_e32 v175, 0xffff0000, v194
	v_max_f32_e32 v1, v1, v1
	v_pk_mul_f32 v[172:173], v[172:173], v[174:175]
	v_max_f32_e32 v1, 0x219392ef, v1
	v_pk_mul_f32 v[116:117], v[116:117], v[172:173]
	v_rcp_f32_e32 v172, v1
	v_and_b32_e32 v1, 0xffff0000, v160
	v_max_f32_e32 v1, v1, v1
	v_max_f32_e32 v1, 0x219392ef, v1
	v_rcp_f32_e32 v173, v1
	v_lshlrev_b32_e32 v1, 16, v161
	v_max_f32_e32 v1, v1, v1
	v_max_f32_e32 v1, 0x219392ef, v1
	v_rcp_f32_e32 v160, v1
	v_and_b32_e32 v1, 0xffff0000, v161
	v_max_f32_e32 v1, v1, v1
	v_max_f32_e32 v1, 0x219392ef, v1
	v_rcp_f32_e32 v161, v1
	v_lshlrev_b32_e32 v174, 16, v195
	v_and_b32_e32 v175, 0xffff0000, v195
	v_pk_mul_f32 v[174:175], v[176:177], v[174:175]
	v_lshlrev_b32_e32 v1, 16, v162
	v_pk_mul_f32 v[118:119], v[118:119], v[174:175]
	s_waitcnt vmcnt(9)
	v_lshlrev_b32_e32 v174, 16, v156
	v_and_b32_e32 v175, 0xffff0000, v156
	v_lshlrev_b32_e32 v156, 16, v157
	v_and_b32_e32 v157, 0xffff0000, v157
	v_max_f32_e32 v1, v1, v1
	v_pk_mul_f32 v[156:157], v[160:161], v[156:157]
	v_max_f32_e32 v1, 0x219392ef, v1
	v_pk_mul_f32 v[114:115], v[114:115], v[156:157]
	v_rcp_f32_e32 v156, v1
	v_and_b32_e32 v1, 0xffff0000, v162
	v_max_f32_e32 v1, v1, v1
	v_max_f32_e32 v1, 0x219392ef, v1
	v_rcp_f32_e32 v157, v1
	v_lshlrev_b32_e32 v1, 16, v163
	v_max_f32_e32 v1, v1, v1
	v_max_f32_e32 v1, 0x219392ef, v1
	v_rcp_f32_e32 v162, v1
	v_and_b32_e32 v1, 0xffff0000, v163
	v_max_f32_e32 v1, v1, v1
	v_max_f32_e32 v1, 0x219392ef, v1
	v_rcp_f32_e32 v163, v1
	s_waitcnt vmcnt(8)
	v_lshlrev_b32_e32 v1, 16, v144
	v_lshlrev_b32_e32 v160, 16, v158
	v_and_b32_e32 v161, 0xffff0000, v158
	v_max_f32_e32 v1, v1, v1
	v_pk_mul_f32 v[156:157], v[156:157], v[160:161]
	v_max_f32_e32 v1, 0x219392ef, v1
	v_pk_mul_f32 v[108:109], v[108:109], v[156:157]
	v_rcp_f32_e32 v156, v1
	v_and_b32_e32 v1, 0xffff0000, v144
	v_max_f32_e32 v1, v1, v1
	v_max_f32_e32 v1, 0x219392ef, v1
	v_rcp_f32_e32 v157, v1
	v_lshlrev_b32_e32 v1, 16, v145
	v_max_f32_e32 v1, v1, v1
	v_max_f32_e32 v1, 0x219392ef, v1
	v_rcp_f32_e32 v144, v1
	v_and_b32_e32 v1, 0xffff0000, v145
	v_max_f32_e32 v1, v1, v1
	v_max_f32_e32 v1, 0x219392ef, v1
	v_rcp_f32_e32 v145, v1
	v_lshlrev_b32_e32 v158, 16, v159
	v_and_b32_e32 v159, 0xffff0000, v159
	v_pk_mul_f32 v[158:159], v[162:163], v[158:159]
	v_lshlrev_b32_e32 v1, 16, v146
	v_pk_mul_f32 v[110:111], v[110:111], v[158:159]
	v_lshlrev_b32_e32 v158, 16, v140
	v_and_b32_e32 v159, 0xffff0000, v140
	v_lshlrev_b32_e32 v140, 16, v141
	v_and_b32_e32 v141, 0xffff0000, v141
	v_max_f32_e32 v1, v1, v1
	v_pk_mul_f32 v[140:141], v[144:145], v[140:141]
	v_max_f32_e32 v1, 0x219392ef, v1
	v_pk_mul_f32 v[106:107], v[106:107], v[140:141]
	v_rcp_f32_e32 v140, v1
	v_and_b32_e32 v1, 0xffff0000, v146
	v_max_f32_e32 v1, v1, v1
	v_max_f32_e32 v1, 0x219392ef, v1
	v_rcp_f32_e32 v141, v1
	v_lshlrev_b32_e32 v1, 16, v147
	v_max_f32_e32 v1, v1, v1
	v_max_f32_e32 v1, 0x219392ef, v1
	v_rcp_f32_e32 v146, v1
	v_and_b32_e32 v1, 0xffff0000, v147
	v_max_f32_e32 v1, v1, v1
	v_max_f32_e32 v1, 0x219392ef, v1
	v_rcp_f32_e32 v147, v1
	v_lshlrev_b32_e32 v144, 16, v142
	v_and_b32_e32 v145, 0xffff0000, v142
	v_lshlrev_b32_e32 v142, 16, v143
	v_and_b32_e32 v143, 0xffff0000, v143
	v_pk_mul_f32 v[142:143], v[146:147], v[142:143]
	s_waitcnt vmcnt(5)
	v_lshlrev_b32_e32 v1, 16, v184
	v_pk_mul_f32 v[102:103], v[102:103], v[142:143]
	v_add_co_u32_e32 v142, vcc, s43, v220
	v_max_f32_e32 v1, v1, v1
	v_pk_mul_f32 v[140:141], v[140:141], v[144:145]
	v_addc_co_u32_e32 v143, vcc, 0, v221, vcc
	v_max_f32_e32 v1, 0x219392ef, v1
	v_pk_mul_f32 v[100:101], v[100:101], v[140:141]
	v_lshl_add_u64 v[140:141], v[220:221], 0, s[10:11]
	v_lshl_add_u64 v[144:145], v[220:221], 0, s[12:13]
	v_add_co_u32_e32 v146, vcc, s44, v220
	v_rcp_f32_e32 v220, v1
	v_and_b32_e32 v1, 0xffff0000, v184
	v_max_f32_e32 v1, v1, v1
	v_max_f32_e32 v1, 0x219392ef, v1
	v_addc_co_u32_e32 v147, vcc, 0, v221, vcc
	v_rcp_f32_e32 v221, v1
	v_lshlrev_b32_e32 v1, 16, v185
	v_max_f32_e32 v1, v1, v1
	v_max_f32_e32 v1, 0x219392ef, v1
	v_max_f32_e32 v196, v196, v196
	v_rcp_f32_e32 v184, v1
	v_and_b32_e32 v1, 0xffff0000, v185
	v_max_f32_e32 v196, 0x219392ef, v196
	v_max_f32_e32 v1, v1, v1
	v_rcp_f32_e32 v179, v196
	v_max_f32_e32 v1, 0x219392ef, v1
	v_rcp_f32_e32 v185, v1
	v_lshlrev_b32_e32 v1, 16, v186
	v_pk_mul_f32 v[178:179], v[178:179], v[226:227]
	v_lshlrev_b32_e32 v226, 16, v180
	v_and_b32_e32 v227, 0xffff0000, v180
	v_lshlrev_b32_e32 v180, 16, v181
	v_and_b32_e32 v181, 0xffff0000, v181
	v_max_f32_e32 v1, v1, v1
	v_pk_mul_f32 v[180:181], v[184:185], v[180:181]
	v_max_f32_e32 v1, 0x219392ef, v1
	v_pk_mul_f32 v[98:99], v[98:99], v[180:181]
	v_rcp_f32_e32 v180, v1
	v_and_b32_e32 v1, 0xffff0000, v186
	v_max_f32_e32 v1, v1, v1
	v_max_f32_e32 v1, 0x219392ef, v1
	v_rcp_f32_e32 v181, v1
	v_lshlrev_b32_e32 v1, 16, v187
	v_max_f32_e32 v1, v1, v1
	v_max_f32_e32 v1, 0x219392ef, v1
	v_rcp_f32_e32 v186, v1
	v_and_b32_e32 v1, 0xffff0000, v187
	v_max_f32_e32 v1, v1, v1
	v_max_f32_e32 v1, 0x219392ef, v1
	v_rcp_f32_e32 v187, v1
	s_waitcnt vmcnt(4)
	v_lshlrev_b32_e32 v1, 16, v168
	v_lshlrev_b32_e32 v184, 16, v182
	v_and_b32_e32 v185, 0xffff0000, v182
	v_max_f32_e32 v1, v1, v1
	v_pk_mul_f32 v[180:181], v[180:181], v[184:185]
	v_max_f32_e32 v1, 0x219392ef, v1
	v_pk_mul_f32 v[92:93], v[92:93], v[180:181]
	v_rcp_f32_e32 v180, v1
	v_and_b32_e32 v1, 0xffff0000, v168
	v_pk_mul_f32 v[172:173], v[172:173], v[174:175]
	v_max_f32_e32 v1, v1, v1
	v_pk_mul_f32 v[128:129], v[128:129], v[178:179]
	v_pk_mul_f32 v[112:113], v[112:113], v[172:173]
	global_load_dwordx4 v[192:195], v[140:141], off offset:2048
	global_load_dwordx4 v[172:175], v[140:141], off offset:256
	global_load_dwordx4 v[188:191], v[142:143], off
	global_load_dwordx4 v[176:179], v[140:141], off offset:2304
	v_max_f32_e32 v1, 0x219392ef, v1
	v_rcp_f32_e32 v181, v1
	v_lshlrev_b32_e32 v1, 16, v169
	v_max_f32_e32 v1, v1, v1
	v_max_f32_e32 v1, 0x219392ef, v1
	v_rcp_f32_e32 v168, v1
	v_and_b32_e32 v1, 0xffff0000, v169
	v_max_f32_e32 v1, v1, v1
	v_max_f32_e32 v1, 0x219392ef, v1
	v_rcp_f32_e32 v169, v1
	v_lshlrev_b32_e32 v182, 16, v183
	v_and_b32_e32 v183, 0xffff0000, v183
	v_pk_mul_f32 v[182:183], v[186:187], v[182:183]
	v_lshlrev_b32_e32 v1, 16, v170
	v_pk_mul_f32 v[94:95], v[94:95], v[182:183]
	v_lshlrev_b32_e32 v182, 16, v164
	v_and_b32_e32 v183, 0xffff0000, v164
	v_lshlrev_b32_e32 v164, 16, v165
	v_and_b32_e32 v165, 0xffff0000, v165
	v_max_f32_e32 v1, v1, v1
	v_pk_mul_f32 v[164:165], v[168:169], v[164:165]
	v_max_f32_e32 v1, 0x219392ef, v1
	v_pk_mul_f32 v[90:91], v[90:91], v[164:165]
	v_rcp_f32_e32 v164, v1
	v_and_b32_e32 v1, 0xffff0000, v170
	v_max_f32_e32 v1, v1, v1
	v_max_f32_e32 v1, 0x219392ef, v1
	v_rcp_f32_e32 v165, v1
	v_lshlrev_b32_e32 v1, 16, v171
	v_max_f32_e32 v1, v1, v1
	v_max_f32_e32 v1, 0x219392ef, v1
	v_rcp_f32_e32 v170, v1
	v_and_b32_e32 v1, 0xffff0000, v171
	v_max_f32_e32 v1, v1, v1
	v_max_f32_e32 v1, 0x219392ef, v1
	v_rcp_f32_e32 v171, v1
	s_waitcnt vmcnt(5)
	v_lshlrev_b32_e32 v1, 16, v152
	v_lshlrev_b32_e32 v168, 16, v166
	v_and_b32_e32 v169, 0xffff0000, v166
	v_max_f32_e32 v1, v1, v1
	v_pk_mul_f32 v[164:165], v[164:165], v[168:169]
	v_max_f32_e32 v1, 0x219392ef, v1
	v_pk_mul_f32 v[84:85], v[84:85], v[164:165]
	v_rcp_f32_e32 v164, v1
	v_and_b32_e32 v1, 0xffff0000, v152
	v_max_f32_e32 v1, v1, v1
	v_max_f32_e32 v1, 0x219392ef, v1
	v_rcp_f32_e32 v165, v1
	v_lshlrev_b32_e32 v1, 16, v153
	v_max_f32_e32 v1, v1, v1
	v_max_f32_e32 v1, 0x219392ef, v1
	v_rcp_f32_e32 v152, v1
	v_and_b32_e32 v1, 0xffff0000, v153
	v_max_f32_e32 v1, v1, v1
	v_max_f32_e32 v1, 0x219392ef, v1
	v_rcp_f32_e32 v153, v1
	v_lshlrev_b32_e32 v166, 16, v167
	v_and_b32_e32 v167, 0xffff0000, v167
	v_pk_mul_f32 v[166:167], v[170:171], v[166:167]
	v_lshlrev_b32_e32 v1, 16, v154
	v_pk_mul_f32 v[86:87], v[86:87], v[166:167]
	v_lshlrev_b32_e32 v166, 16, v148
	v_and_b32_e32 v167, 0xffff0000, v148
	v_lshlrev_b32_e32 v148, 16, v149
	v_and_b32_e32 v149, 0xffff0000, v149
	v_max_f32_e32 v1, v1, v1
	v_pk_mul_f32 v[148:149], v[152:153], v[148:149]
	v_max_f32_e32 v1, 0x219392ef, v1
	v_pk_mul_f32 v[82:83], v[82:83], v[148:149]
	v_rcp_f32_e32 v148, v1
	v_and_b32_e32 v1, 0xffff0000, v154
	v_max_f32_e32 v1, v1, v1
	v_max_f32_e32 v1, 0x219392ef, v1
	v_rcp_f32_e32 v149, v1
	v_lshlrev_b32_e32 v1, 16, v155
	v_max_f32_e32 v1, v1, v1
	v_max_f32_e32 v1, 0x219392ef, v1
	v_rcp_f32_e32 v154, v1
	v_and_b32_e32 v1, 0xffff0000, v155
	v_max_f32_e32 v1, v1, v1
	v_max_f32_e32 v1, 0x219392ef, v1
	v_pk_mul_f32 v[156:157], v[156:157], v[158:159]
	v_rcp_f32_e32 v155, v1
	s_waitcnt vmcnt(4)
	v_lshlrev_b32_e32 v1, 16, v136
	v_pk_mul_f32 v[104:105], v[104:105], v[156:157]
	global_load_dwordx4 v[160:163], v[144:145], off offset:2048
	global_load_dwordx4 v[140:143], v[144:145], off offset:256
	global_load_dwordx4 v[156:159], v[146:147], off
	s_nop 0
	global_load_dwordx4 v[144:147], v[144:145], off offset:2304
	v_lshlrev_b32_e32 v152, 16, v150
	v_and_b32_e32 v153, 0xffff0000, v150
	v_max_f32_e32 v1, v1, v1
	v_pk_mul_f32 v[148:149], v[148:149], v[152:153]
	v_max_f32_e32 v1, 0x219392ef, v1
	v_pk_mul_f32 v[76:77], v[76:77], v[148:149]
	v_rcp_f32_e32 v148, v1
	v_and_b32_e32 v1, 0xffff0000, v136
	v_max_f32_e32 v1, v1, v1
	v_max_f32_e32 v1, 0x219392ef, v1
	v_rcp_f32_e32 v149, v1
	v_lshlrev_b32_e32 v1, 16, v137
	v_max_f32_e32 v1, v1, v1
	v_max_f32_e32 v1, 0x219392ef, v1
	v_rcp_f32_e32 v136, v1
	v_and_b32_e32 v1, 0xffff0000, v137
	v_max_f32_e32 v1, v1, v1
	v_max_f32_e32 v1, 0x219392ef, v1
	v_rcp_f32_e32 v137, v1
	v_lshlrev_b32_e32 v150, 16, v151
	v_and_b32_e32 v151, 0xffff0000, v151
	v_pk_mul_f32 v[150:151], v[154:155], v[150:151]
	v_lshlrev_b32_e32 v1, 16, v138
	v_pk_mul_f32 v[78:79], v[78:79], v[150:151]
	v_lshlrev_b32_e32 v150, 16, v132
	v_and_b32_e32 v151, 0xffff0000, v132
	v_lshlrev_b32_e32 v132, 16, v133
	v_and_b32_e32 v133, 0xffff0000, v133
	v_max_f32_e32 v1, v1, v1
	v_pk_mul_f32 v[132:133], v[136:137], v[132:133]
	v_max_f32_e32 v1, 0x219392ef, v1
	v_pk_mul_f32 v[74:75], v[74:75], v[132:133]
	v_rcp_f32_e32 v132, v1
	v_and_b32_e32 v1, 0xffff0000, v138
	v_max_f32_e32 v1, v1, v1
	v_max_f32_e32 v1, 0x219392ef, v1
	v_rcp_f32_e32 v133, v1
	v_lshlrev_b32_e32 v1, 16, v139
	v_lshlrev_b32_e32 v136, 16, v134
	v_and_b32_e32 v137, 0xffff0000, v134
	v_max_f32_e32 v1, v1, v1
	v_max_f32_e32 v1, 0x219392ef, v1
	v_pk_mul_f32 v[132:133], v[132:133], v[136:137]
	v_rcp_f32_e32 v138, v1
	v_and_b32_e32 v1, 0xffff0000, v139
	v_pk_mul_f32 v[68:69], v[68:69], v[132:133]
	v_add_u32_e32 v132, 0xa0, v218
	v_max_f32_e32 v1, v1, v1
	v_ashrrev_i32_e32 v133, 31, v132
	v_max_f32_e32 v1, 0x219392ef, v1
	v_lshlrev_b64 v[132:133], 12, v[132:133]
	v_pk_mul_f32 v[180:181], v[180:181], v[182:183]
	v_pk_mul_f32 v[164:165], v[164:165], v[166:167]
	v_rcp_f32_e32 v139, v1
	v_lshl_add_u64 v[132:133], v[2:3], 0, v[132:133]
	v_pk_mul_f32 v[88:89], v[88:89], v[180:181]
	v_pk_mul_f32 v[80:81], v[80:81], v[164:165]
	global_load_dwordx4 v[180:183], v[132:133], off
	global_load_dwordx4 v[164:167], v[132:133], off offset:256
	global_load_dwordx4 v[184:187], v[132:133], off offset:2048
	global_load_dwordx4 v[168:171], v[132:133], off offset:2304
	v_add_u32_e32 v132, 0xb0, v218
	v_ashrrev_i32_e32 v133, 31, v132
	s_waitcnt vmcnt(11)
	v_lshlrev_b32_e32 v1, 16, v192
	v_lshlrev_b32_e32 v134, 16, v135
	v_and_b32_e32 v135, 0xffff0000, v135
	v_lshlrev_b64 v[132:133], 12, v[132:133]
	v_max_f32_e32 v1, v1, v1
	v_pk_mul_f32 v[148:149], v[148:149], v[150:151]
	v_pk_mul_f32 v[134:135], v[138:139], v[134:135]
	v_lshl_add_u64 v[2:3], v[2:3], 0, v[132:133]
	v_max_f32_e32 v1, 0x219392ef, v1
	v_pk_mul_f32 v[72:73], v[72:73], v[148:149]
	v_pk_mul_f32 v[70:71], v[70:71], v[134:135]
	global_load_dwordx4 v[148:151], v[2:3], off
	global_load_dwordx4 v[132:135], v[2:3], off offset:256
	global_load_dwordx4 v[152:155], v[2:3], off offset:2048
	global_load_dwordx4 v[136:139], v[2:3], off offset:2304
	v_rcp_f32_e32 v2, v1
	v_and_b32_e32 v1, 0xffff0000, v192
	v_max_f32_e32 v1, v1, v1
	v_max_f32_e32 v1, 0x219392ef, v1
	v_rcp_f32_e32 v3, v1
	v_lshlrev_b32_e32 v1, 16, v193
	v_max_f32_e32 v1, v1, v1
	v_max_f32_e32 v1, 0x219392ef, v1
	v_rcp_f32_e32 v192, v1
	v_and_b32_e32 v1, 0xffff0000, v193
	v_max_f32_e32 v1, v1, v1
	v_max_f32_e32 v1, 0x219392ef, v1
	v_rcp_f32_e32 v193, v1
	v_lshlrev_b32_e32 v1, 16, v194
	s_waitcnt vmcnt(13)
	v_lshlrev_b32_e32 v218, 16, v188
	v_and_b32_e32 v219, 0xffff0000, v188
	v_max_f32_e32 v1, v1, v1
	v_pk_mul_f32 v[2:3], v[2:3], v[218:219]
	v_max_f32_e32 v1, 0x219392ef, v1
	v_pk_mul_f32 v[64:65], v[64:65], v[2:3]
	v_rcp_f32_e32 v2, v1
	v_and_b32_e32 v1, 0xffff0000, v194
	v_max_f32_e32 v1, v1, v1
	v_max_f32_e32 v1, 0x219392ef, v1
	v_rcp_f32_e32 v3, v1
	v_lshlrev_b32_e32 v1, 16, v195
	v_max_f32_e32 v1, v1, v1
	v_lshlrev_b32_e32 v188, 16, v189
	v_and_b32_e32 v189, 0xffff0000, v189
	v_max_f32_e32 v1, 0x219392ef, v1
	v_pk_mul_f32 v[188:189], v[192:193], v[188:189]
	v_rcp_f32_e32 v192, v1
	v_and_b32_e32 v1, 0xffff0000, v195
	v_max_f32_e32 v1, v1, v1
	v_max_f32_e32 v1, 0x219392ef, v1
	v_rcp_f32_e32 v193, v1
	s_waitcnt vmcnt(12)
	v_lshlrev_b32_e32 v1, 16, v176
	v_pk_mul_f32 v[66:67], v[66:67], v[188:189]
	v_lshlrev_b32_e32 v188, 16, v190
	v_and_b32_e32 v189, 0xffff0000, v190
	v_max_f32_e32 v1, v1, v1
	v_pk_mul_f32 v[2:3], v[2:3], v[188:189]
	v_max_f32_e32 v1, 0x219392ef, v1
	v_pk_mul_f32 v[60:61], v[60:61], v[2:3]
	v_rcp_f32_e32 v2, v1
	v_and_b32_e32 v1, 0xffff0000, v176
	v_max_f32_e32 v1, v1, v1
	v_max_f32_e32 v1, 0x219392ef, v1
	v_rcp_f32_e32 v3, v1
	v_lshlrev_b32_e32 v1, 16, v177
	v_max_f32_e32 v1, v1, v1
	v_max_f32_e32 v1, 0x219392ef, v1
	v_rcp_f32_e32 v176, v1
	v_and_b32_e32 v1, 0xffff0000, v177
	v_max_f32_e32 v1, v1, v1
	v_lshlrev_b32_e32 v188, 16, v191
	v_and_b32_e32 v189, 0xffff0000, v191
	v_max_f32_e32 v1, 0x219392ef, v1
	v_pk_mul_f32 v[188:189], v[192:193], v[188:189]
	v_rcp_f32_e32 v177, v1
	v_lshlrev_b32_e32 v1, 16, v178
	v_pk_mul_f32 v[62:63], v[62:63], v[188:189]
	v_lshlrev_b32_e32 v188, 16, v172
	v_and_b32_e32 v189, 0xffff0000, v172
	v_max_f32_e32 v1, v1, v1
	v_pk_mul_f32 v[2:3], v[2:3], v[188:189]
	v_max_f32_e32 v1, 0x219392ef, v1
	v_pk_mul_f32 v[56:57], v[56:57], v[2:3]
	v_rcp_f32_e32 v2, v1
	v_and_b32_e32 v1, 0xffff0000, v178
	v_max_f32_e32 v1, v1, v1
	v_max_f32_e32 v1, 0x219392ef, v1
	v_rcp_f32_e32 v3, v1
	v_lshlrev_b32_e32 v1, 16, v179
	v_max_f32_e32 v1, v1, v1
	v_lshlrev_b32_e32 v172, 16, v173
	v_and_b32_e32 v173, 0xffff0000, v173
	v_max_f32_e32 v1, 0x219392ef, v1
	v_pk_mul_f32 v[172:173], v[176:177], v[172:173]
	v_rcp_f32_e32 v176, v1
	v_and_b32_e32 v1, 0xffff0000, v179
	v_max_f32_e32 v1, v1, v1
	v_max_f32_e32 v1, 0x219392ef, v1
	v_rcp_f32_e32 v177, v1
	s_waitcnt vmcnt(11)
	v_lshlrev_b32_e32 v1, 16, v160
	v_pk_mul_f32 v[58:59], v[58:59], v[172:173]
	v_lshlrev_b32_e32 v172, 16, v174
	v_and_b32_e32 v173, 0xffff0000, v174
	v_max_f32_e32 v1, v1, v1
	v_pk_mul_f32 v[2:3], v[2:3], v[172:173]
	v_max_f32_e32 v1, 0x219392ef, v1
	v_pk_mul_f32 v[52:53], v[52:53], v[2:3]
	v_rcp_f32_e32 v2, v1
	v_and_b32_e32 v1, 0xffff0000, v160
	v_max_f32_e32 v1, v1, v1
	v_max_f32_e32 v1, 0x219392ef, v1
	v_rcp_f32_e32 v3, v1
	v_lshlrev_b32_e32 v1, 16, v161
	v_max_f32_e32 v1, v1, v1
	v_max_f32_e32 v1, 0x219392ef, v1
	v_rcp_f32_e32 v160, v1
	v_and_b32_e32 v1, 0xffff0000, v161
	v_max_f32_e32 v1, v1, v1
	v_lshlrev_b32_e32 v172, 16, v175
	v_and_b32_e32 v173, 0xffff0000, v175
	v_max_f32_e32 v1, 0x219392ef, v1
	v_pk_mul_f32 v[172:173], v[176:177], v[172:173]
	v_rcp_f32_e32 v161, v1
	v_lshlrev_b32_e32 v1, 16, v162
	v_pk_mul_f32 v[54:55], v[54:55], v[172:173]
	s_waitcnt vmcnt(9)
	v_lshlrev_b32_e32 v172, 16, v156
	v_and_b32_e32 v173, 0xffff0000, v156
	v_max_f32_e32 v1, v1, v1
	v_pk_mul_f32 v[2:3], v[2:3], v[172:173]
	v_max_f32_e32 v1, 0x219392ef, v1
	v_pk_mul_f32 v[48:49], v[48:49], v[2:3]
	v_rcp_f32_e32 v2, v1
	v_and_b32_e32 v1, 0xffff0000, v162
	v_max_f32_e32 v1, v1, v1
	v_max_f32_e32 v1, 0x219392ef, v1
	v_rcp_f32_e32 v3, v1
	v_lshlrev_b32_e32 v1, 16, v163
	v_max_f32_e32 v1, v1, v1
	v_lshlrev_b32_e32 v156, 16, v157
	v_and_b32_e32 v157, 0xffff0000, v157
	v_max_f32_e32 v1, 0x219392ef, v1
	v_pk_mul_f32 v[156:157], v[160:161], v[156:157]
	v_rcp_f32_e32 v160, v1
	v_and_b32_e32 v1, 0xffff0000, v163
	v_max_f32_e32 v1, v1, v1
	v_max_f32_e32 v1, 0x219392ef, v1
	v_rcp_f32_e32 v161, v1
	s_waitcnt vmcnt(8)
	v_lshlrev_b32_e32 v1, 16, v144
	v_pk_mul_f32 v[50:51], v[50:51], v[156:157]
	v_lshlrev_b32_e32 v156, 16, v158
	v_and_b32_e32 v157, 0xffff0000, v158
	v_max_f32_e32 v1, v1, v1
	v_pk_mul_f32 v[2:3], v[2:3], v[156:157]
	v_max_f32_e32 v1, 0x219392ef, v1
	v_pk_mul_f32 v[44:45], v[44:45], v[2:3]
	v_rcp_f32_e32 v2, v1
	v_and_b32_e32 v1, 0xffff0000, v144
	v_max_f32_e32 v1, v1, v1
	v_max_f32_e32 v1, 0x219392ef, v1
	v_rcp_f32_e32 v3, v1
	v_lshlrev_b32_e32 v1, 16, v145
	v_max_f32_e32 v1, v1, v1
	v_max_f32_e32 v1, 0x219392ef, v1
	v_rcp_f32_e32 v144, v1
	v_and_b32_e32 v1, 0xffff0000, v145
	v_max_f32_e32 v1, v1, v1
	v_lshlrev_b32_e32 v156, 16, v159
	v_and_b32_e32 v157, 0xffff0000, v159
	v_max_f32_e32 v1, 0x219392ef, v1
	v_pk_mul_f32 v[156:157], v[160:161], v[156:157]
	v_rcp_f32_e32 v145, v1
	v_lshlrev_b32_e32 v1, 16, v146
	v_pk_mul_f32 v[46:47], v[46:47], v[156:157]
	v_lshlrev_b32_e32 v156, 16, v140
	v_and_b32_e32 v157, 0xffff0000, v140
	v_max_f32_e32 v1, v1, v1
	v_pk_mul_f32 v[2:3], v[2:3], v[156:157]
	v_max_f32_e32 v1, 0x219392ef, v1
	v_pk_mul_f32 v[40:41], v[40:41], v[2:3]
	v_rcp_f32_e32 v2, v1
	v_and_b32_e32 v1, 0xffff0000, v146
	v_max_f32_e32 v1, v1, v1
	v_max_f32_e32 v1, 0x219392ef, v1
	v_rcp_f32_e32 v3, v1
	v_lshlrev_b32_e32 v1, 16, v147
	v_max_f32_e32 v1, v1, v1
	v_lshlrev_b32_e32 v140, 16, v141
	v_and_b32_e32 v141, 0xffff0000, v141
	v_max_f32_e32 v1, 0x219392ef, v1
	v_pk_mul_f32 v[140:141], v[144:145], v[140:141]
	v_rcp_f32_e32 v144, v1
	v_and_b32_e32 v1, 0xffff0000, v147
	v_max_f32_e32 v1, v1, v1
	v_max_f32_e32 v1, 0x219392ef, v1
	v_rcp_f32_e32 v145, v1
	s_waitcnt vmcnt(5)
	v_lshlrev_b32_e32 v1, 16, v184
	v_pk_mul_f32 v[42:43], v[42:43], v[140:141]
	v_lshlrev_b32_e32 v140, 16, v142
	v_and_b32_e32 v141, 0xffff0000, v142
	v_max_f32_e32 v1, v1, v1
	v_pk_mul_f32 v[2:3], v[2:3], v[140:141]
	v_max_f32_e32 v1, 0x219392ef, v1
	v_pk_mul_f32 v[36:37], v[36:37], v[2:3]
	v_rcp_f32_e32 v2, v1
	v_and_b32_e32 v1, 0xffff0000, v184
	v_max_f32_e32 v1, v1, v1
	v_max_f32_e32 v1, 0x219392ef, v1
	v_rcp_f32_e32 v3, v1
	v_lshlrev_b32_e32 v1, 16, v185
	v_max_f32_e32 v1, v1, v1
	v_max_f32_e32 v1, 0x219392ef, v1
	v_rcp_f32_e32 v142, v1
	v_and_b32_e32 v1, 0xffff0000, v185
	v_max_f32_e32 v1, v1, v1
	v_lshlrev_b32_e32 v140, 16, v143
	v_and_b32_e32 v141, 0xffff0000, v143
	v_max_f32_e32 v1, 0x219392ef, v1
	v_pk_mul_f32 v[140:141], v[144:145], v[140:141]
	v_rcp_f32_e32 v143, v1
	v_lshlrev_b32_e32 v1, 16, v186
	v_pk_mul_f32 v[38:39], v[38:39], v[140:141]
	v_lshlrev_b32_e32 v140, 16, v180
	v_and_b32_e32 v141, 0xffff0000, v180
	v_max_f32_e32 v1, v1, v1
	v_pk_mul_f32 v[2:3], v[2:3], v[140:141]
	v_max_f32_e32 v1, 0x219392ef, v1
	v_pk_mul_f32 v[32:33], v[32:33], v[2:3]
	v_rcp_f32_e32 v2, v1
	v_and_b32_e32 v1, 0xffff0000, v186
	v_max_f32_e32 v1, v1, v1
	v_max_f32_e32 v1, 0x219392ef, v1
	v_rcp_f32_e32 v3, v1
	v_lshlrev_b32_e32 v1, 16, v187
	v_max_f32_e32 v1, v1, v1
	v_lshlrev_b32_e32 v140, 16, v181
	v_and_b32_e32 v141, 0xffff0000, v181
	v_max_f32_e32 v1, 0x219392ef, v1
	v_pk_mul_f32 v[140:141], v[142:143], v[140:141]
	v_rcp_f32_e32 v142, v1
	v_and_b32_e32 v1, 0xffff0000, v187
	v_max_f32_e32 v1, v1, v1
	v_max_f32_e32 v1, 0x219392ef, v1
	v_rcp_f32_e32 v143, v1
	s_waitcnt vmcnt(4)
	v_lshlrev_b32_e32 v1, 16, v168
	v_pk_mul_f32 v[34:35], v[34:35], v[140:141]
	v_lshlrev_b32_e32 v140, 16, v182
	v_and_b32_e32 v141, 0xffff0000, v182
	v_max_f32_e32 v1, v1, v1
	v_pk_mul_f32 v[2:3], v[2:3], v[140:141]
	v_max_f32_e32 v1, 0x219392ef, v1
	v_pk_mul_f32 v[28:29], v[28:29], v[2:3]
	v_rcp_f32_e32 v2, v1
	v_and_b32_e32 v1, 0xffff0000, v168
	v_max_f32_e32 v1, v1, v1
	v_max_f32_e32 v1, 0x219392ef, v1
	v_rcp_f32_e32 v3, v1
	v_lshlrev_b32_e32 v1, 16, v169
	v_max_f32_e32 v1, v1, v1
	v_lshlrev_b32_e32 v140, 16, v183
	v_and_b32_e32 v141, 0xffff0000, v183
	v_max_f32_e32 v1, 0x219392ef, v1
	v_pk_mul_f32 v[140:141], v[142:143], v[140:141]
	v_rcp_f32_e32 v142, v1
	v_and_b32_e32 v1, 0xffff0000, v169
	v_max_f32_e32 v1, v1, v1
	v_max_f32_e32 v1, 0x219392ef, v1
	v_rcp_f32_e32 v143, v1
	v_lshlrev_b32_e32 v1, 16, v170
	v_pk_mul_f32 v[30:31], v[30:31], v[140:141]
	v_lshlrev_b32_e32 v140, 16, v164
	v_and_b32_e32 v141, 0xffff0000, v164
	v_max_f32_e32 v1, v1, v1
	v_pk_mul_f32 v[2:3], v[2:3], v[140:141]
	v_max_f32_e32 v1, 0x219392ef, v1
	v_pk_mul_f32 v[24:25], v[24:25], v[2:3]
	v_rcp_f32_e32 v2, v1
	v_and_b32_e32 v1, 0xffff0000, v170
	v_max_f32_e32 v1, v1, v1
	v_max_f32_e32 v1, 0x219392ef, v1
	v_rcp_f32_e32 v3, v1
	v_lshlrev_b32_e32 v1, 16, v171
	v_max_f32_e32 v1, v1, v1
	v_lshlrev_b32_e32 v140, 16, v165
	v_and_b32_e32 v141, 0xffff0000, v165
	v_max_f32_e32 v1, 0x219392ef, v1
	v_pk_mul_f32 v[140:141], v[142:143], v[140:141]
	v_rcp_f32_e32 v142, v1
	v_and_b32_e32 v1, 0xffff0000, v171
	v_max_f32_e32 v1, v1, v1
	v_max_f32_e32 v1, 0x219392ef, v1
	v_rcp_f32_e32 v143, v1
	s_waitcnt vmcnt(1)
	v_lshlrev_b32_e32 v1, 16, v152
	v_pk_mul_f32 v[26:27], v[26:27], v[140:141]
	v_lshlrev_b32_e32 v140, 16, v166
	v_and_b32_e32 v141, 0xffff0000, v166
	v_max_f32_e32 v1, v1, v1
	v_pk_mul_f32 v[2:3], v[2:3], v[140:141]
	v_max_f32_e32 v1, 0x219392ef, v1
	v_pk_mul_f32 v[20:21], v[20:21], v[2:3]
	v_rcp_f32_e32 v2, v1
	v_and_b32_e32 v1, 0xffff0000, v152
	v_max_f32_e32 v1, v1, v1
	v_max_f32_e32 v1, 0x219392ef, v1
	v_rcp_f32_e32 v3, v1
	v_lshlrev_b32_e32 v1, 16, v153
	v_max_f32_e32 v1, v1, v1
	v_lshlrev_b32_e32 v140, 16, v167
	v_and_b32_e32 v141, 0xffff0000, v167
	v_max_f32_e32 v1, 0x219392ef, v1
	v_pk_mul_f32 v[140:141], v[142:143], v[140:141]
	v_rcp_f32_e32 v142, v1
	v_and_b32_e32 v1, 0xffff0000, v153
	v_max_f32_e32 v1, v1, v1
	v_max_f32_e32 v1, 0x219392ef, v1
	v_rcp_f32_e32 v143, v1
	v_lshlrev_b32_e32 v1, 16, v154
	v_pk_mul_f32 v[22:23], v[22:23], v[140:141]
	v_lshlrev_b32_e32 v140, 16, v148
	v_and_b32_e32 v141, 0xffff0000, v148
	v_max_f32_e32 v1, v1, v1
	v_pk_mul_f32 v[2:3], v[2:3], v[140:141]
	v_max_f32_e32 v1, 0x219392ef, v1
	v_pk_mul_f32 v[16:17], v[16:17], v[2:3]
	v_rcp_f32_e32 v2, v1
	v_and_b32_e32 v1, 0xffff0000, v154
	v_max_f32_e32 v1, v1, v1
	v_max_f32_e32 v1, 0x219392ef, v1
	v_rcp_f32_e32 v3, v1
	v_lshlrev_b32_e32 v1, 16, v155
	v_max_f32_e32 v1, v1, v1
	v_lshlrev_b32_e32 v140, 16, v149
	v_and_b32_e32 v141, 0xffff0000, v149
	v_max_f32_e32 v1, 0x219392ef, v1
	v_pk_mul_f32 v[140:141], v[142:143], v[140:141]
	v_rcp_f32_e32 v142, v1
	v_and_b32_e32 v1, 0xffff0000, v155
	v_max_f32_e32 v1, v1, v1
	v_max_f32_e32 v1, 0x219392ef, v1
	v_rcp_f32_e32 v143, v1
	s_waitcnt vmcnt(0)
	v_lshlrev_b32_e32 v1, 16, v136
	v_pk_mul_f32 v[18:19], v[18:19], v[140:141]
	v_lshlrev_b32_e32 v140, 16, v150
	v_and_b32_e32 v141, 0xffff0000, v150
	v_max_f32_e32 v1, v1, v1
	v_pk_mul_f32 v[2:3], v[2:3], v[140:141]
	v_max_f32_e32 v1, 0x219392ef, v1
	v_pk_mul_f32 v[12:13], v[12:13], v[2:3]
	v_rcp_f32_e32 v2, v1
	v_and_b32_e32 v1, 0xffff0000, v136
	v_max_f32_e32 v1, v1, v1
	v_max_f32_e32 v1, 0x219392ef, v1
	v_rcp_f32_e32 v3, v1
	v_lshlrev_b32_e32 v1, 16, v137
	v_max_f32_e32 v1, v1, v1
	v_max_f32_e32 v1, 0x219392ef, v1
	v_rcp_f32_e32 v136, v1
	v_and_b32_e32 v1, 0xffff0000, v137
	v_max_f32_e32 v1, v1, v1
	v_lshlrev_b32_e32 v140, 16, v151
	v_and_b32_e32 v141, 0xffff0000, v151
	v_max_f32_e32 v1, 0x219392ef, v1
	v_pk_mul_f32 v[140:141], v[142:143], v[140:141]
	v_rcp_f32_e32 v137, v1
	v_lshlrev_b32_e32 v1, 16, v138
	v_pk_mul_f32 v[14:15], v[14:15], v[140:141]
	v_lshlrev_b32_e32 v140, 16, v132
	v_and_b32_e32 v141, 0xffff0000, v132
	v_max_f32_e32 v1, v1, v1
	v_pk_mul_f32 v[2:3], v[2:3], v[140:141]
	v_max_f32_e32 v1, 0x219392ef, v1
	v_pk_mul_f32 v[8:9], v[8:9], v[2:3]
	v_rcp_f32_e32 v2, v1
	v_and_b32_e32 v1, 0xffff0000, v138
	v_max_f32_e32 v1, v1, v1
	v_max_f32_e32 v1, 0x219392ef, v1
	v_rcp_f32_e32 v3, v1
	v_lshlrev_b32_e32 v1, 16, v139
	v_max_f32_e32 v1, v1, v1
	v_lshlrev_b32_e32 v132, 16, v133
	v_and_b32_e32 v133, 0xffff0000, v133
	v_max_f32_e32 v1, 0x219392ef, v1
	v_pk_mul_f32 v[132:133], v[136:137], v[132:133]
	v_rcp_f32_e32 v136, v1
	v_and_b32_e32 v1, 0xffff0000, v139
	v_max_f32_e32 v1, v1, v1
	v_max_f32_e32 v1, 0x219392ef, v1
	v_rcp_f32_e32 v137, v1
	v_pk_mul_f32 v[10:11], v[10:11], v[132:133]
	v_lshlrev_b32_e32 v132, 16, v134
	v_and_b32_e32 v133, 0xffff0000, v134
	v_pk_mul_f32 v[2:3], v[2:3], v[132:133]
	v_lshlrev_b32_e32 v132, 16, v135
	v_and_b32_e32 v133, 0xffff0000, v135
	v_pk_mul_f32 v[220:221], v[220:221], v[226:227]
	v_pk_mul_f32 v[132:133], v[136:137], v[132:133]
	v_pk_mul_f32 v[96:97], v[96:97], v[220:221]
	v_pk_mul_f32 v[6:7], v[6:7], v[132:133]
	v_pk_mul_f32 v[4:5], v[4:5], v[2:3]
	s_branch .LBB0_535
